# mLSTM pass1 inner loop: the four gate-table LDS reads of each half issued together (lgkmcnt counted) instead of three serialized read-wait pairs
# speedup vs baseline: 1.0057x; 1.0038x over previous
; #define LAS __attribute__((address_space(3)))
; #define MFMA32(a, b, c) __builtin_amdgcn_mfma_f32_32x32x16_bf16((a), (b), (c), 0, 0, 0)
; #define PACK8(v, base) __builtin_bit_cast(bf16x8, (u32x4){pk2((v)[(base)], (v)[(base) + 1]), pk2((v)[(base) + 2], (v)[(base) + 3]), pk2((v)[(base) + 4], (v)[(base) + 5]), pk2((v)[(base) + 6], (v)[(base) + 7])})
; __device__ __forceinline__ void mlstm_pass1(const bf16_t* PR, const bf16_t* QC, const bf16_t* KC, const float* Gt, const float* gain, bf16_t* Y, LAS unsigned char* lds, ...
;     ...
;                 for (int tt = 0; tt < 2; ++tt) {
;                     const LAS unsigned char* qb0 = lds + ML_QT + (32 * tt + r) * KROW + 8 * h;
;                     f32x16 hi_, ha, S0, S1;
; #pragma unroll
;                     for (int e = 0; e < 16; ++e) { hi_[e] = 0.f; ha[e] = 0.f; S0[e] = 0.f; S1[e] = 0.f; }
;                     const LAS unsigned char* kb0 = lds + ML_KT + r * KROW + 8 * h;
; #pragma unroll
;                     for (int i = 0; i < 4; ++i)
; #pragma unroll
;                         for (int s = 0; s < 2; ++s) {
;                             const bf16x8 q = lds2x8(qb0 + 64 * i + 32 * s, qb0 + 64 * i + 32 * s + 16);
;                             hi_ = MFMA32(PACK8(C[i], 8 * s), q, hi_);
;                             S0 = MFMA32(lds2x8(kb0 + 64 * i + 32 * s, kb0 + 64 * i + 32 * s + 16), q, S0);
;                             S1 = MFMA32(lds2x8(kb0 + 32 * KROW + 64 * i + 32 * s, kb0 + 32 * KROW + 64 * i + 32 * s + 16), q, S1);
;                             if (s == 1) LFENCE();
;                         }
;                     const float bt = __shfl(bsum, 32 * tt + r);
;                     const LAS unsigned char* vb = vtb + (4 * h + (li >> 2)) * vstr + (16 * gg + 4 * (li & 3)) * 2;
;                     {
; #pragma unroll
;                         for (int g4 = 0; g4 < 4; ++g4) { const f32x4 cv = *(const LAS f32x4*)(cs_t + 8 * g4 + 4 * h);
; #pragma unroll
;                             for (int e = 0; e < 4; ++e) { const int sl = 8 * g4 + 4 * h + e; const bool ok = (tt == 1) || (sl <= r);
;                                 S0[4 * g4 + e] = ok ? S0[4 * g4 + e] * __builtin_amdgcn_exp2f((bt + cv[e]) * LOG2E) : 0.f; } }
;                         ha = MFMA32(tr2(vb, vb + 8 * vstr), PACK8(S0, 0), ha);
;                         ha = MFMA32(tr2(vb + 16 * vstr, vb + 24 * vstr), PACK8(S0, 8), ha);
.LBB0_476:
	v_lshl_or_b32 v186, s75, 5, v142
	v_mad_u32_u24 v187, v186, s33, v165
	ds_read2_b64 v[80:83], v187 offset1:2
	v_cvt_pk_bf16_f32 v64, v32, v33
	v_cvt_pk_bf16_f32 v65, v34, v35
	v_cvt_pk_bf16_f32 v66, v36, v37
	v_cvt_pk_bf16_f32 v67, v38, v39
	ds_read2_b64 v[84:87], v180 offset1:2
	s_waitcnt lgkmcnt(0)
	v_mfma_f32_32x32x16_bf16 v[64:79], v[64:67], v[80:83], 0
	ds_read2_b64 v[192:195], v187 offset0:4 offset1:6
	v_add_u32_e32 v188, 0x2000, v180
	s_or_b64 vcc, s[94:95], s[8:9]
	v_mfma_f32_32x32x16_bf16 v[96:111], v[84:87], v[80:83], 0
	ds_read2_b64 v[84:87], v188 offset0:64 offset1:66
	ds_read2_b64 v[208:211], v180 offset0:4 offset1:6
	ds_read2_b64 v[216:219], v188 offset0:68 offset1:70
	v_cvt_pk_bf16_f32 v196, v40, v41
	v_cvt_pk_bf16_f32 v197, v42, v43
	v_cvt_pk_bf16_f32 v198, v44, v45
	v_cvt_pk_bf16_f32 v199, v46, v47
	ds_read2_b64 v[204:207], v187 offset0:8 offset1:10
	ds_read2_b64 v[212:215], v180 offset0:8 offset1:10
	ds_read2_b64 v[220:223], v188 offset0:72 offset1:74
	s_waitcnt lgkmcnt(3)
	v_mfma_f32_32x32x16_bf16 v[64:79], v[196:199], v[192:195], v[64:79]
	v_mfma_f32_32x32x16_bf16 v[96:111], v[208:211], v[192:195], v[96:111]
	v_mfma_f32_32x32x16_bf16 v[80:95], v[84:87], v[80:83], 0
	v_mfma_f32_32x32x16_bf16 v[80:95], v[216:219], v[192:195], v[80:95]
	v_cvt_pk_bf16_f32 v196, v48, v49
	v_cvt_pk_bf16_f32 v197, v50, v51
	v_cvt_pk_bf16_f32 v198, v52, v53
	v_cvt_pk_bf16_f32 v199, v54, v55
	ds_read2_b64 v[192:195], v187 offset0:12 offset1:14
	ds_read2_b64 v[208:211], v180 offset0:12 offset1:14
	ds_read2_b64 v[216:219], v188 offset0:76 offset1:78
	s_waitcnt lgkmcnt(3)
	v_mfma_f32_32x32x16_bf16 v[64:79], v[196:199], v[204:207], v[64:79]
	v_mfma_f32_32x32x16_bf16 v[96:111], v[212:215], v[204:207], v[96:111]
	v_mfma_f32_32x32x16_bf16 v[80:95], v[220:223], v[204:207], v[80:95]
	v_cvt_pk_bf16_f32 v196, v56, v57
	v_cvt_pk_bf16_f32 v197, v58, v59
	v_cvt_pk_bf16_f32 v198, v60, v61
	v_cvt_pk_bf16_f32 v199, v62, v63
	ds_read2_b64 v[204:207], v187 offset0:16 offset1:18
	ds_read2_b64 v[212:215], v180 offset0:16 offset1:18
	ds_read2_b64 v[220:223], v188 offset0:80 offset1:82
	s_waitcnt lgkmcnt(3)
	v_mfma_f32_32x32x16_bf16 v[64:79], v[196:199], v[192:195], v[64:79]
	v_mfma_f32_32x32x16_bf16 v[96:111], v[208:211], v[192:195], v[96:111]
	v_mfma_f32_32x32x16_bf16 v[80:95], v[216:219], v[192:195], v[80:95]
	v_cvt_pk_bf16_f32 v196, v16, v17
	v_cvt_pk_bf16_f32 v197, v18, v19
	v_cvt_pk_bf16_f32 v198, v20, v21
	v_cvt_pk_bf16_f32 v199, v22, v23
	ds_read2_b64 v[192:195], v187 offset0:20 offset1:22
	ds_read2_b64 v[208:211], v180 offset0:20 offset1:22
	ds_read2_b64 v[216:219], v188 offset0:84 offset1:86
	s_waitcnt lgkmcnt(3)
	v_mfma_f32_32x32x16_bf16 v[64:79], v[196:199], v[204:207], v[64:79]
	v_mfma_f32_32x32x16_bf16 v[96:111], v[212:215], v[204:207], v[96:111]
	v_mfma_f32_32x32x16_bf16 v[80:95], v[220:223], v[204:207], v[80:95]
	v_cvt_pk_bf16_f32 v196, v24, v25
	v_cvt_pk_bf16_f32 v197, v26, v27
	v_cvt_pk_bf16_f32 v198, v28, v29
	v_cvt_pk_bf16_f32 v199, v30, v31
	ds_read2_b64 v[204:207], v187 offset0:24 offset1:26
	ds_read2_b64 v[212:215], v180 offset0:24 offset1:26
	ds_read2_b64 v[220:223], v188 offset0:88 offset1:90
	s_waitcnt lgkmcnt(3)
	v_mfma_f32_32x32x16_bf16 v[64:79], v[196:199], v[192:195], v[64:79]
	v_mfma_f32_32x32x16_bf16 v[96:111], v[208:211], v[192:195], v[96:111]
	v_mfma_f32_32x32x16_bf16 v[80:95], v[216:219], v[192:195], v[80:95]
	v_cvt_pk_bf16_f32 v196, v0, v1
	v_cvt_pk_bf16_f32 v197, v2, v3
	v_cvt_pk_bf16_f32 v198, v4, v5
	v_cvt_pk_bf16_f32 v199, v6, v7
	ds_read2_b64 v[192:195], v187 offset0:28 offset1:30
	ds_read2_b64 v[208:211], v180 offset0:28 offset1:30
	ds_read2_b64 v[216:219], v188 offset0:92 offset1:94
	s_waitcnt lgkmcnt(3)
	v_mfma_f32_32x32x16_bf16 v[64:79], v[196:199], v[204:207], v[64:79]
	v_mfma_f32_32x32x16_bf16 v[96:111], v[212:215], v[204:207], v[96:111]
	v_mfma_f32_32x32x16_bf16 v[80:95], v[220:223], v[204:207], v[80:95]
	v_cvt_pk_bf16_f32 v196, v8, v9
	v_cvt_pk_bf16_f32 v197, v10, v11
	v_cvt_pk_bf16_f32 v198, v12, v13
	v_cvt_pk_bf16_f32 v199, v14, v15
	v_or_b32_e32 v187, v186, v143
	v_lshlrev_b32_e32 v187, 2, v187
	ds_bpermute_b32 v187, v187, v185
	s_waitcnt lgkmcnt(0)
	v_mfma_f32_32x32x16_bf16 v[64:79], v[196:199], v[192:195], v[64:79]
	v_mfma_f32_32x32x16_bf16 v[96:111], v[208:211], v[192:195], v[96:111]
	v_mfma_f32_32x32x16_bf16 v[80:95], v[216:219], v[192:195], v[80:95]
	ds_read_b128 v[192:195], v167 offset:62464
	ds_read_b128 v[196:199], v167 offset:62496
	ds_read_b128 v[224:227], v167 offset:62528
	ds_read_b128 v[228:231], v167 offset:62560
	s_waitcnt lgkmcnt(2)
	v_add_f32_e32 v188, v192, v187
	v_mul_f32_e32 v188, 0x3fb8aa3b, v188
	v_exp_f32_e32 v188, v188
	s_nop 2
	v_mul_f32_e32 v96, v96, v188
	v_add_f32_e32 v188, v193, v187
	v_mul_f32_e32 v188, 0x3fb8aa3b, v188
	v_exp_f32_e32 v188, v188
	v_cndmask_b32_e32 v96, 0, v96, vcc
	s_or_b64 vcc, s[94:95], s[10:11]
	v_mul_f32_e32 v97, v97, v188
	v_add_f32_e32 v188, v194, v187
	v_mul_f32_e32 v188, 0x3fb8aa3b, v188
	v_exp_f32_e32 v188, v188
	v_cndmask_b32_e32 v97, 0, v97, vcc
	s_or_b64 vcc, s[94:95], s[12:13]
	v_mul_f32_e32 v98, v98, v188
	v_cndmask_b32_e32 v188, 0, v98, vcc
	v_add_f32_e32 v98, v195, v187
	v_mul_f32_e32 v98, 0x3fb8aa3b, v98
	v_exp_f32_e32 v98, v98
	s_or_b64 vcc, s[94:95], s[14:15]
	v_mul_f32_e32 v98, v99, v98
	v_cndmask_b32_e32 v191, 0, v98, vcc
	v_add_f32_e32 v98, v196, v187
	v_mul_f32_e32 v98, 0x3fb8aa3b, v98
	v_exp_f32_e32 v98, v98
	s_or_b64 vcc, s[94:95], s[16:17]
	v_mul_f32_e32 v98, v100, v98
	v_cndmask_b32_e32 v192, 0, v98, vcc
	v_add_f32_e32 v98, v197, v187
	v_mul_f32_e32 v98, 0x3fb8aa3b, v98
	v_exp_f32_e32 v98, v98
	s_or_b64 vcc, s[94:95], s[18:19]
	v_mul_f32_e32 v98, v101, v98
	v_cndmask_b32_e32 v193, 0, v98, vcc
	v_add_f32_e32 v98, v198, v187
	v_mul_f32_e32 v98, 0x3fb8aa3b, v98
	v_exp_f32_e32 v98, v98
	s_or_b64 vcc, s[94:95], s[20:21]
	v_mul_f32_e32 v98, v102, v98
	v_cndmask_b32_e32 v194, 0, v98, vcc
	v_add_f32_e32 v98, v199, v187
	v_mul_f32_e32 v98, 0x3fb8aa3b, v98
	v_exp_f32_e32 v98, v98
	s_or_b64 vcc, s[94:95], s[22:23]
	v_mul_f32_e32 v98, v103, v98
	v_cndmask_b32_e32 v195, 0, v98, vcc
	s_nop 0
	s_or_b64 vcc, s[94:95], s[24:25]
	s_waitcnt lgkmcnt(1)
; #define LAS __attribute__((address_space(3)))
; #define MFMA32(a, b, c) __builtin_amdgcn_mfma_f32_32x32x16_bf16((a), (b), (c), 0, 0, 0)
; #define PACK8(v, base) __builtin_bit_cast(bf16x8, (u32x4){pk2((v)[(base)], (v)[(base) + 1]), pk2((v)[(base) + 2], (v)[(base) + 3]), pk2((v)[(base) + 4], (v)[(base) + 5]), pk2((v)[(base) + 6], (v)[(base) + 7])})
; __device__ __forceinline__ void mlstm_pass1(const bf16_t* PR, const bf16_t* QC, const bf16_t* KC, const float* Gt, const float* gain, bf16_t* Y, LAS unsigned char* lds, ...
;     ...
;                         for (int g4 = 0; g4 < 4; ++g4) { const f32x4 cv = *(const LAS f32x4*)(cs_t + 8 * g4 + 4 * h);
; #pragma unroll
;                             for (int e = 0; e < 4; ++e) { const int sl = 8 * g4 + 4 * h + e; const bool ok = (tt == 1) || (sl <= r);
;                                 S0[4 * g4 + e] = ok ? S0[4 * g4 + e] * __builtin_amdgcn_exp2f((bt + cv[e]) * LOG2E) : 0.f; } }
;                         ha = MFMA32(tr2(vb, vb + 8 * vstr), PACK8(S0, 0), ha);
;                         ha = MFMA32(tr2(vb + 16 * vstr, vb + 24 * vstr), PACK8(S0, 8), ha);
;                     }
;                     if (tt == 1) {
; #pragma unroll
;                         for (int g4 = 0; g4 < 4; ++g4) { const f32x4 cv = *(const LAS f32x4*)(cs_t + 32 + 8 * g4 + 4 * h);
; #pragma unroll
;                             for (int e = 0; e < 4; ++e) { const int sl = 8 * g4 + 4 * h + e; const bool ok = (sl <= r);
;                                 S1[4 * g4 + e] = ok ? S1[4 * g4 + e] * __builtin_amdgcn_exp2f((bt + cv[e]) * LOG2E) : 0.f; } }
;                         ha = MFMA32(tr2(vb + 32 * vstr, vb + 40 * vstr), PACK8(S1, 0), ha);
;                         ha = MFMA32(tr2(vb + 48 * vstr, vb + 56 * vstr), PACK8(S1, 8), ha);
;                     }
	v_add_f32_e32 v98, v224, v187
	v_mul_f32_e32 v98, 0x3fb8aa3b, v98
	v_exp_f32_e32 v98, v98
	s_nop 0
	v_mul_f32_e32 v98, v104, v98
	v_cndmask_b32_e32 v196, 0, v98, vcc
	v_add_f32_e32 v98, v225, v187
	v_mul_f32_e32 v98, 0x3fb8aa3b, v98
	v_exp_f32_e32 v98, v98
	s_or_b64 vcc, s[94:95], s[26:27]
	v_mul_f32_e32 v98, v105, v98
	v_cndmask_b32_e32 v197, 0, v98, vcc
	v_add_f32_e32 v98, v226, v187
	v_mul_f32_e32 v98, 0x3fb8aa3b, v98
	v_exp_f32_e32 v98, v98
	s_or_b64 vcc, s[94:95], s[28:29]
	v_mul_f32_e32 v98, v106, v98
	v_cndmask_b32_e32 v198, 0, v98, vcc
	v_add_f32_e32 v98, v227, v187
	v_mul_f32_e32 v98, 0x3fb8aa3b, v98
	v_exp_f32_e32 v98, v98
	s_or_b64 vcc, s[94:95], s[30:31]
	v_mul_f32_e32 v98, v107, v98
	v_cndmask_b32_e32 v199, 0, v98, vcc
	s_nop 0
	s_or_b64 vcc, s[94:95], s[34:35]
	s_waitcnt lgkmcnt(0)
	v_add_f32_e32 v98, v228, v187
	v_mul_f32_e32 v98, 0x3fb8aa3b, v98
	v_exp_f32_e32 v98, v98
	s_nop 0
	v_mul_f32_e32 v98, v108, v98
	v_cndmask_b32_e32 v200, 0, v98, vcc
	v_add_f32_e32 v98, v229, v187
	v_mul_f32_e32 v98, 0x3fb8aa3b, v98
	v_exp_f32_e32 v98, v98
	s_or_b64 vcc, s[94:95], s[36:37]
	v_mul_f32_e32 v98, v109, v98
	v_cndmask_b32_e32 v201, 0, v98, vcc
	v_add_f32_e32 v98, v230, v187
	v_mul_f32_e32 v98, 0x3fb8aa3b, v98
	v_exp_f32_e32 v98, v98
	s_or_b64 vcc, s[94:95], s[38:39]
	v_add_u32_e32 v100, s72, v166
	v_mul_f32_e32 v98, v110, v98
	v_cndmask_b32_e32 v202, 0, v98, vcc
	v_add_f32_e32 v98, v231, v187
	v_mul_f32_e32 v98, 0x3fb8aa3b, v98
	v_exp_f32_e32 v98, v98
	s_or_b64 vcc, s[94:95], s[40:41]
	ds_read_b64_tr_b16 v[100:101], v100
	v_mul_f32_e32 v98, v111, v98
	v_cndmask_b32_e32 v203, 0, v98, vcc
	ds_read_b64_tr_b16 v[98:99], v166
	v_cvt_pk_bf16_f32 v102, v96, v97
	v_cvt_pk_bf16_f32 v103, v188, v191
	v_add_u32_e32 v188, s73, v166
	v_cvt_pk_bf16_f32 v104, v192, v193
	v_cvt_pk_bf16_f32 v105, v194, v195
	ds_read_b64_tr_b16 v[192:193], v188
	v_add_u32_e32 v188, s4, v166
	ds_read_b64_tr_b16 v[194:195], v188
	s_waitcnt lgkmcnt(0)
	v_mfma_f32_32x32x16_bf16 v[96:111], v[98:101], v[102:105], 0
	v_cvt_pk_bf16_f32 v196, v196, v197
	v_cvt_pk_bf16_f32 v197, v198, v199
	v_cvt_pk_bf16_f32 v198, v200, v201
	v_cvt_pk_bf16_f32 v199, v202, v203
	s_andn2_b64 vcc, exec, s[94:95]
	v_mfma_f32_32x32x16_bf16 v[96:111], v[192:195], v[196:199], v[96:111]
	s_cbranch_vccnz .LBB0_478
	ds_read_b128 v[192:195], v167 offset:62592
	ds_read_b128 v[196:199], v167 offset:62624
	ds_read_b128 v[224:227], v167 offset:62656
	ds_read_b128 v[228:231], v167 offset:62688
	s_waitcnt lgkmcnt(2)
	v_add_f32_e32 v188, v192, v187
	v_mul_f32_e32 v188, 0x3fb8aa3b, v188
	v_exp_f32_e32 v188, v188
	s_nop 0
	v_mul_f32_e32 v80, v80, v188
	v_cndmask_b32_e64 v188, v80, 0, s[42:43]
	v_add_f32_e32 v80, v193, v187
	v_mul_f32_e32 v80, 0x3fb8aa3b, v80
	v_exp_f32_e32 v80, v80
	s_nop 0
	v_mul_f32_e32 v80, v81, v80
	v_cndmask_b32_e64 v191, 0, v80, s[10:11]
	v_add_f32_e32 v80, v194, v187
	v_mul_f32_e32 v80, 0x3fb8aa3b, v80
	v_exp_f32_e32 v80, v80
	s_nop 0
	v_mul_f32_e32 v80, v82, v80
	v_cndmask_b32_e64 v192, v80, 0, s[44:45]
	v_add_f32_e32 v80, v195, v187
	v_mul_f32_e32 v80, 0x3fb8aa3b, v80
	v_exp_f32_e32 v80, v80
	s_nop 0
	v_mul_f32_e32 v80, v83, v80
	v_cndmask_b32_e64 v193, v80, 0, s[46:47]
	v_add_f32_e32 v80, v196, v187
	v_mul_f32_e32 v80, 0x3fb8aa3b, v80
	v_exp_f32_e32 v80, v80
	s_nop 0
	v_mul_f32_e32 v80, v84, v80
	v_cndmask_b32_e64 v194, v80, 0, s[48:49]
	v_add_f32_e32 v80, v197, v187
	v_mul_f32_e32 v80, 0x3fb8aa3b, v80
	v_exp_f32_e32 v80, v80
	s_nop 0
	v_mul_f32_e32 v80, v85, v80
	v_cndmask_b32_e64 v195, v80, 0, s[50:51]
	v_add_f32_e32 v80, v198, v187
	v_mul_f32_e32 v80, 0x3fb8aa3b, v80
	v_exp_f32_e32 v80, v80
	s_nop 0
	v_mul_f32_e32 v80, v86, v80
	v_cndmask_b32_e64 v196, v80, 0, s[52:53]
	v_add_f32_e32 v80, v199, v187
	v_mul_f32_e32 v80, 0x3fb8aa3b, v80
	v_exp_f32_e32 v80, v80
	s_nop 0
	v_mul_f32_e32 v80, v87, v80
	v_cndmask_b32_e64 v87, v80, 0, s[54:55]
	s_nop 0
	s_waitcnt lgkmcnt(1)
	v_add_f32_e32 v80, v224, v187
	v_mul_f32_e32 v80, 0x3fb8aa3b, v80
	v_exp_f32_e32 v80, v80
	s_nop 0
	v_mul_f32_e32 v80, v88, v80
	v_cndmask_b32_e64 v88, v80, 0, s[56:57]
	v_add_f32_e32 v80, v225, v187
	v_mul_f32_e32 v80, 0x3fb8aa3b, v80
	v_exp_f32_e32 v80, v80
	s_nop 0
	v_mul_f32_e32 v80, v89, v80
	v_cndmask_b32_e64 v89, v80, 0, s[58:59]
	v_add_f32_e32 v80, v226, v187
	v_mul_f32_e32 v80, 0x3fb8aa3b, v80
	v_exp_f32_e32 v80, v80
	s_nop 0
	v_mul_f32_e32 v80, v90, v80
	v_cndmask_b32_e64 v90, v80, 0, s[60:61]
	v_add_f32_e32 v80, v227, v187
	v_mul_f32_e32 v80, 0x3fb8aa3b, v80
	v_exp_f32_e32 v80, v80
	s_nop 0
	v_mul_f32_e32 v80, v91, v80
	v_cndmask_b32_e64 v91, v80, 0, s[62:63]
	s_nop 0
	s_waitcnt lgkmcnt(0)
	v_add_f32_e32 v80, v228, v187
	v_mul_f32_e32 v80, 0x3fb8aa3b, v80
	v_exp_f32_e32 v80, v80
	s_nop 0
	v_mul_f32_e32 v80, v92, v80
	v_cndmask_b32_e64 v92, v80, 0, s[64:65]
	v_add_f32_e32 v80, v229, v187
	v_mul_f32_e32 v80, 0x3fb8aa3b, v80
	v_exp_f32_e32 v80, v80
	s_nop 0
	v_mul_f32_e32 v80, v93, v80
	v_cndmask_b32_e64 v93, v80, 0, s[66:67]
	v_add_f32_e32 v80, v230, v187
	v_mul_f32_e32 v80, 0x3fb8aa3b, v80
	v_exp_f32_e32 v80, v80
	v_add_u32_e32 v82, s6, v166
	v_mul_f32_e32 v80, v94, v80
	v_cndmask_b32_e64 v94, v80, 0, s[68:69]
	v_add_f32_e32 v80, v231, v187
	v_mul_f32_e32 v80, 0x3fb8aa3b, v80
	v_exp_f32_e32 v80, v80
	ds_read_b64_tr_b16 v[82:83], v82
	v_mul_f32_e32 v80, v95, v80
	v_cndmask_b32_e64 v95, v80, 0, s[70:71]
	v_add_u32_e32 v80, s5, v166
	ds_read_b64_tr_b16 v[80:81], v80
	v_cvt_pk_bf16_f32 v84, v188, v191
	v_cvt_pk_bf16_f32 v85, v192, v193
	v_cvt_pk_bf16_f32 v86, v194, v195
	v_cvt_pk_bf16_f32 v87, v196, v87
	s_waitcnt lgkmcnt(0)
	v_mfma_f32_32x32x16_bf16 v[96:111], v[80:83], v[84:87], v[96:111]
	v_add_u32_e32 v80, s7, v166
	v_add_u32_e32 v82, s92, v166
	ds_read_b64_tr_b16 v[80:81], v80
	ds_read_b64_tr_b16 v[82:83], v82
	v_cvt_pk_bf16_f32 v84, v88, v89
	v_cvt_pk_bf16_f32 v85, v90, v91
	v_cvt_pk_bf16_f32 v86, v92, v93
	v_cvt_pk_bf16_f32 v87, v94, v95
	s_waitcnt lgkmcnt(0)
	v_mfma_f32_32x32x16_bf16 v[96:111], v[80:83], v[84:87], v[96:111]
